# grid barrier: the last-arriving XCD leader bumps every XCD's release word, other leaders wait on their own XCD's word (one poll hop fewer)
# baseline (speedup 1.0000x reference)
; __device__ __forceinline__ unsigned xb_ld(unsigned* p)              { return __hip_atomic_load(p, __ATOMIC_RELAXED, __HIP_MEMORY_SCOPE_AGENT); }
; __device__ __forceinline__ unsigned xb_add(unsigned* p, unsigned v) { return __hip_atomic_fetch_add(p, v, __ATOMIC_RELAXED, __HIP_MEMORY_SCOPE_AGENT); }
; #define XB_SPIN(cond, bar) do { unsigned _sp = 0; while (cond) { __builtin_amdgcn_s_sleep(1); \
;     if ((++_sp & 255u) == 0u) { if (xb_ld(&(bar)[XB_TMO])) break; if (_sp > XB_SPIN_CAP) { atomicAdd(&(bar)[XB_TMO], 1u); break; } } } } while (0)
; __device__ __forceinline__ void xcd_barrier(const XcdBarrier& b) {
;     ...
;         const unsigned old = xb_add(&bar[XB_XSUB(b.x)], 1u);
;         const unsigned gen = old / nloc;
;         if (old + 1u == (gen + 1u) * nloc) {
;             __builtin_amdgcn_fence(__ATOMIC_RELEASE, "agent");
;             asm volatile("s_waitcnt vmcnt(0)" ::: "memory");
;             const unsigned og = xb_add(&bar[XB_TOP], 1u);
;             const unsigned tg = og / nx;
;             if (og + 1u == (tg + 1u) * nx) xb_add(&bar[XB_TOPGEN], 1u);
;             else XB_SPIN(xb_ld(&bar[XB_TOPGEN]) == tg, bar);
.LBB0_154:
	s_or_b64 exec, exec, s[6:7]
	v_cvt_f32_u32_e32 v3, v1
	s_waitcnt vmcnt(0)
	v_readfirstlane_b32 s2, v2
	s_mov_b64 s[6:7], -1
	v_rcp_iflag_f32_e32 v3, v3
	v_add_u32_e32 v0, s2, v0
	v_add_u32_e32 v4, 1, v0
	v_readlane_b32 s2, v253, 17
	v_mul_f32_e32 v2, 0x4f7ffffe, v3
	v_cvt_u32_f32_e32 v2, v2
	v_sub_u32_e32 v3, 0, v1
	v_readlane_b32 s3, v253, 18
	v_mul_lo_u32 v3, v3, v2
	v_mul_hi_u32 v3, v2, v3
	v_add_u32_e32 v2, v2, v3
	v_mul_hi_u32 v2, v0, v2
	v_mul_lo_u32 v3, v2, v1
	v_sub_u32_e32 v0, v0, v3
	v_add_u32_e32 v5, 1, v2
	v_cmp_ge_u32_e32 vcc, v0, v1
	v_sub_u32_e32 v3, v0, v1
	s_nop 0
	v_cndmask_b32_e32 v2, v2, v5, vcc
	v_cndmask_b32_e32 v0, v0, v3, vcc
	v_add_u32_e32 v3, 1, v2
	v_cmp_ge_u32_e32 vcc, v0, v1
	s_nop 1
	v_cndmask_b32_e32 v2, v2, v3, vcc
	v_mul_lo_u32 v0, v1, v2
	v_add_u32_e32 v0, v0, v1
	v_cmp_ne_u32_e32 vcc, v4, v0
	v_mov_b64_e32 v[0:1], s[2:3]
	s_and_saveexec_b64 s[2:3], vcc
	s_cbranch_execz .LBB0_166
	v_readlane_b32 s6, v253, 13
	v_readlane_b32 s7, v253, 14
	s_mov_b64 s[8:9], 0
	s_nop 3
	global_load_dword v0, v129, s[6:7] sc1
	s_waitcnt vmcnt(0)
	v_cmp_eq_u32_e32 vcc, v0, v2
	s_and_saveexec_b64 s[6:7], vcc
	s_cbranch_execz .LBB0_165
	s_mov_b32 s19, 1
	s_branch .LBB0_158

; __device__ __forceinline__ unsigned xb_ld(unsigned* p)              { return __hip_atomic_load(p, __ATOMIC_RELAXED, __HIP_MEMORY_SCOPE_AGENT); }
; __device__ __forceinline__ unsigned xb_add(unsigned* p, unsigned v) { return __hip_atomic_fetch_add(p, v, __ATOMIC_RELAXED, __HIP_MEMORY_SCOPE_AGENT); }
; #define XB_SPIN(cond, bar) do { unsigned _sp = 0; while (cond) { __builtin_amdgcn_s_sleep(1); \
;     if ((++_sp & 255u) == 0u) { if (xb_ld(&(bar)[XB_TMO])) break; if (_sp > XB_SPIN_CAP) { atomicAdd(&(bar)[XB_TMO], 1u); break; } } } } while (0)
; __device__ __forceinline__ void xcd_barrier(const XcdBarrier& b) {
;     ...
;             const unsigned og = xb_add(&bar[XB_TOP], 1u);
;             const unsigned tg = og / nx;
;             if (og + 1u == (tg + 1u) * nx) xb_add(&bar[XB_TOPGEN], 1u);
;             else XB_SPIN(xb_ld(&bar[XB_TOPGEN]) == tg, bar);
.LBB0_162:
	v_readlane_b32 s12, v253, 13
	v_readlane_b32 s13, v253, 14
	s_add_i32 s19, s19, 1
	s_mov_b64 s[14:15], -1
	s_nop 2
	global_load_dword v0, v129, s[12:13] sc1
	s_waitcnt vmcnt(0)
	v_cmp_ne_u32_e32 vcc, v0, v2
	s_orn2_b64 s[12:13], vcc, exec
	s_branch .LBB0_157

; __device__ __forceinline__ unsigned xb_ld(unsigned* p)              { return __hip_atomic_load(p, __ATOMIC_RELAXED, __HIP_MEMORY_SCOPE_AGENT); }
; __device__ __forceinline__ unsigned xb_add(unsigned* p, unsigned v) { return __hip_atomic_fetch_add(p, v, __ATOMIC_RELAXED, __HIP_MEMORY_SCOPE_AGENT); }
; #define XB_SPIN(cond, bar) do { unsigned _sp = 0; while (cond) { __builtin_amdgcn_s_sleep(1); \
;     if ((++_sp & 255u) == 0u) { if (xb_ld(&(bar)[XB_TMO])) break; if (_sp > XB_SPIN_CAP) { atomicAdd(&(bar)[XB_TMO], 1u); break; } } } } while (0)
; __device__ __forceinline__ void xcd_barrier(const XcdBarrier& b) {
;     ...
;             const unsigned og = xb_add(&bar[XB_TOP], 1u);
;             const unsigned tg = og / nx;
;             if (og + 1u == (tg + 1u) * nx) xb_add(&bar[XB_TOPGEN], 1u);
;             else XB_SPIN(xb_ld(&bar[XB_TOPGEN]) == tg, bar);
;             __builtin_amdgcn_fence(__ATOMIC_ACQUIRE, "agent");
;             xb_add(&bar[XB_XGEN(b.x)], 1u);
;             asm volatile("s_waitcnt vmcnt(0)" ::: "memory");
.LBB0_166:
	s_or_b64 exec, exec, s[2:3]
	s_and_saveexec_b64 s[2:3], s[6:7]
	s_cbranch_execz .LBB0_168
	global_atomic_add v[0:1], v207, off
	v_readlane_b32 s6, v253, 17
	v_readlane_b32 s7, v253, 18
	s_sub_u32 s6, s6, 0x1100
	s_subb_u32 s7, s7, 0
	global_atomic_add v129, v207, s[6:7]
	global_atomic_add v129, v207, s[6:7] offset:256
	global_atomic_add v129, v207, s[6:7] offset:512
	global_atomic_add v129, v207, s[6:7] offset:768
	global_atomic_add v129, v207, s[6:7] offset:1024
	global_atomic_add v129, v207, s[6:7] offset:1280
	global_atomic_add v129, v207, s[6:7] offset:1536
	global_atomic_add v129, v207, s[6:7] offset:1792
	global_atomic_add v129, v207, s[6:7] offset:2048
	global_atomic_add v129, v207, s[6:7] offset:2304
	global_atomic_add v129, v207, s[6:7] offset:2560
	global_atomic_add v129, v207, s[6:7] offset:2816
	global_atomic_add v129, v207, s[6:7] offset:3072
	global_atomic_add v129, v207, s[6:7] offset:3328
	global_atomic_add v129, v207, s[6:7] offset:3584
	global_atomic_add v129, v207, s[6:7] offset:3840
.LBB0_168:
	s_or_b64 exec, exec, s[2:3]
	v_readlane_b32 s2, v253, 13
	v_readlane_b32 s3, v253, 14
	s_waitcnt vmcnt(0)
	buffer_inv sc1
	s_nop 2
	s_waitcnt vmcnt(0)

; __device__ __forceinline__ unsigned xb_ld(unsigned* p)              { return __hip_atomic_load(p, __ATOMIC_RELAXED, __HIP_MEMORY_SCOPE_AGENT); }
; __device__ __forceinline__ unsigned xb_add(unsigned* p, unsigned v) { return __hip_atomic_fetch_add(p, v, __ATOMIC_RELAXED, __HIP_MEMORY_SCOPE_AGENT); }
; #define XB_SPIN(cond, bar) do { unsigned _sp = 0; while (cond) { __builtin_amdgcn_s_sleep(1); \
;     if ((++_sp & 255u) == 0u) { if (xb_ld(&(bar)[XB_TMO])) break; if (_sp > XB_SPIN_CAP) { atomicAdd(&(bar)[XB_TMO], 1u); break; } } } } while (0)
; __device__ __forceinline__ void xcd_barrier(const XcdBarrier& b) {
;     ...
;         const unsigned old = xb_add(&bar[XB_XSUB(b.x)], 1u);
;         const unsigned gen = old / nloc;
;         if (old + 1u == (gen + 1u) * nloc) {
;             __builtin_amdgcn_fence(__ATOMIC_RELEASE, "agent");
;             asm volatile("s_waitcnt vmcnt(0)" ::: "memory");
;             const unsigned og = xb_add(&bar[XB_TOP], 1u);
;             const unsigned tg = og / nx;
;             if (og + 1u == (tg + 1u) * nx) xb_add(&bar[XB_TOPGEN], 1u);
;             else XB_SPIN(xb_ld(&bar[XB_TOPGEN]) == tg, bar);
.LBB0_210:
	s_or_b64 exec, exec, s[4:5]
	v_cvt_f32_u32_e32 v3, v0
	s_waitcnt vmcnt(0)
	v_readfirstlane_b32 s2, v2
	s_mov_b64 s[4:5], -1
	v_rcp_iflag_f32_e32 v3, v3
	v_add_u32_e32 v1, s2, v1
	v_add_u32_e32 v4, 1, v1
	v_readlane_b32 s2, v253, 17
	v_mul_f32_e32 v2, 0x4f7ffffe, v3
	v_cvt_u32_f32_e32 v2, v2
	v_sub_u32_e32 v3, 0, v0
	v_readlane_b32 s3, v253, 18
	v_mul_lo_u32 v3, v3, v2
	v_mul_hi_u32 v3, v2, v3
	v_add_u32_e32 v2, v2, v3
	v_mul_hi_u32 v2, v1, v2
	v_mul_lo_u32 v3, v2, v0
	v_sub_u32_e32 v1, v1, v3
	v_add_u32_e32 v5, 1, v2
	v_cmp_ge_u32_e32 vcc, v1, v0
	v_sub_u32_e32 v3, v1, v0
	s_nop 0
	v_cndmask_b32_e32 v2, v2, v5, vcc
	v_cndmask_b32_e32 v1, v1, v3, vcc
	v_add_u32_e32 v3, 1, v2
	v_cmp_ge_u32_e32 vcc, v1, v0
	s_nop 1
	v_cndmask_b32_e32 v2, v2, v3, vcc
	v_mul_lo_u32 v1, v0, v2
	v_add_u32_e32 v0, v1, v0
	v_cmp_ne_u32_e32 vcc, v4, v0
	v_mov_b64_e32 v[0:1], s[2:3]
	s_and_saveexec_b64 s[2:3], vcc
	s_cbranch_execz .LBB0_222
	v_readlane_b32 s4, v253, 13
	v_readlane_b32 s5, v253, 14
	s_mov_b64 s[6:7], 0
	s_nop 3
	global_load_dword v0, v129, s[4:5] sc1
	s_waitcnt vmcnt(0)
	v_cmp_eq_u32_e32 vcc, v0, v2
	s_and_saveexec_b64 s[4:5], vcc
	s_cbranch_execz .LBB0_221
	s_mov_b32 s16, 1
	s_branch .LBB0_214

; __device__ __forceinline__ unsigned xb_ld(unsigned* p)              { return __hip_atomic_load(p, __ATOMIC_RELAXED, __HIP_MEMORY_SCOPE_AGENT); }
; __device__ __forceinline__ unsigned xb_add(unsigned* p, unsigned v) { return __hip_atomic_fetch_add(p, v, __ATOMIC_RELAXED, __HIP_MEMORY_SCOPE_AGENT); }
; #define XB_SPIN(cond, bar) do { unsigned _sp = 0; while (cond) { __builtin_amdgcn_s_sleep(1); \
;     if ((++_sp & 255u) == 0u) { if (xb_ld(&(bar)[XB_TMO])) break; if (_sp > XB_SPIN_CAP) { atomicAdd(&(bar)[XB_TMO], 1u); break; } } } } while (0)
; __device__ __forceinline__ void xcd_barrier(const XcdBarrier& b) {
;     ...
;             const unsigned og = xb_add(&bar[XB_TOP], 1u);
;             const unsigned tg = og / nx;
;             if (og + 1u == (tg + 1u) * nx) xb_add(&bar[XB_TOPGEN], 1u);
;             else XB_SPIN(xb_ld(&bar[XB_TOPGEN]) == tg, bar);
.LBB0_218:
	v_readlane_b32 s10, v253, 13
	v_readlane_b32 s11, v253, 14
	s_add_i32 s16, s16, 1
	s_mov_b64 s[12:13], -1
	s_nop 2
	global_load_dword v0, v129, s[10:11] sc1
	s_waitcnt vmcnt(0)
	v_cmp_ne_u32_e32 vcc, v0, v2
	s_orn2_b64 s[10:11], vcc, exec
	s_branch .LBB0_213

; __device__ __forceinline__ unsigned xb_ld(unsigned* p)              { return __hip_atomic_load(p, __ATOMIC_RELAXED, __HIP_MEMORY_SCOPE_AGENT); }
; __device__ __forceinline__ unsigned xb_add(unsigned* p, unsigned v) { return __hip_atomic_fetch_add(p, v, __ATOMIC_RELAXED, __HIP_MEMORY_SCOPE_AGENT); }
; #define XB_SPIN(cond, bar) do { unsigned _sp = 0; while (cond) { __builtin_amdgcn_s_sleep(1); \
;     if ((++_sp & 255u) == 0u) { if (xb_ld(&(bar)[XB_TMO])) break; if (_sp > XB_SPIN_CAP) { atomicAdd(&(bar)[XB_TMO], 1u); break; } } } } while (0)
; __device__ __forceinline__ void xcd_barrier(const XcdBarrier& b) {
;     ...
;             const unsigned og = xb_add(&bar[XB_TOP], 1u);
;             const unsigned tg = og / nx;
;             if (og + 1u == (tg + 1u) * nx) xb_add(&bar[XB_TOPGEN], 1u);
;             else XB_SPIN(xb_ld(&bar[XB_TOPGEN]) == tg, bar);
;             __builtin_amdgcn_fence(__ATOMIC_ACQUIRE, "agent");
;             xb_add(&bar[XB_XGEN(b.x)], 1u);
;             asm volatile("s_waitcnt vmcnt(0)" ::: "memory");
.LBB0_222:
	s_or_b64 exec, exec, s[2:3]
	s_and_saveexec_b64 s[2:3], s[4:5]
	s_cbranch_execz .LBB0_224
	global_atomic_add v[0:1], v207, off
	v_readlane_b32 s4, v253, 17
	v_readlane_b32 s5, v253, 18
	s_sub_u32 s4, s4, 0x1100
	s_subb_u32 s5, s5, 0
	global_atomic_add v129, v207, s[4:5]
	global_atomic_add v129, v207, s[4:5] offset:256
	global_atomic_add v129, v207, s[4:5] offset:512
	global_atomic_add v129, v207, s[4:5] offset:768
	global_atomic_add v129, v207, s[4:5] offset:1024
	global_atomic_add v129, v207, s[4:5] offset:1280
	global_atomic_add v129, v207, s[4:5] offset:1536
	global_atomic_add v129, v207, s[4:5] offset:1792
	global_atomic_add v129, v207, s[4:5] offset:2048
	global_atomic_add v129, v207, s[4:5] offset:2304
	global_atomic_add v129, v207, s[4:5] offset:2560
	global_atomic_add v129, v207, s[4:5] offset:2816
	global_atomic_add v129, v207, s[4:5] offset:3072
	global_atomic_add v129, v207, s[4:5] offset:3328
	global_atomic_add v129, v207, s[4:5] offset:3584
	global_atomic_add v129, v207, s[4:5] offset:3840

; __device__ __forceinline__ unsigned xb_ld(unsigned* p)              { return __hip_atomic_load(p, __ATOMIC_RELAXED, __HIP_MEMORY_SCOPE_AGENT); }
; __device__ __forceinline__ unsigned xb_add(unsigned* p, unsigned v) { return __hip_atomic_fetch_add(p, v, __ATOMIC_RELAXED, __HIP_MEMORY_SCOPE_AGENT); }
; #define XB_SPIN(cond, bar) do { unsigned _sp = 0; while (cond) { __builtin_amdgcn_s_sleep(1); \
;     if ((++_sp & 255u) == 0u) { if (xb_ld(&(bar)[XB_TMO])) break; if (_sp > XB_SPIN_CAP) { atomicAdd(&(bar)[XB_TMO], 1u); break; } } } } while (0)
; __device__ __forceinline__ void xcd_barrier(const XcdBarrier& b) {
;     ...
;         const unsigned old = xb_add(&bar[XB_XSUB(b.x)], 1u);
;         const unsigned gen = old / nloc;
;         if (old + 1u == (gen + 1u) * nloc) {
;             __builtin_amdgcn_fence(__ATOMIC_RELEASE, "agent");
;             asm volatile("s_waitcnt vmcnt(0)" ::: "memory");
;             const unsigned og = xb_add(&bar[XB_TOP], 1u);
;             const unsigned tg = og / nx;
;             if (og + 1u == (tg + 1u) * nx) xb_add(&bar[XB_TOPGEN], 1u);
;             else XB_SPIN(xb_ld(&bar[XB_TOPGEN]) == tg, bar);
.LBB0_331:
	s_or_b64 exec, exec, s[4:5]
	s_waitcnt vmcnt(0)
	v_readfirstlane_b32 s2, v2
	v_cvt_f32_u32_e32 v2, v0
	v_sub_u32_e32 v3, 0, v0
	v_add_u32_e32 v1, s2, v1
	v_readlane_b32 s2, v253, 17
	v_rcp_iflag_f32_e32 v2, v2
	v_readlane_b32 s3, v253, 18
	s_mov_b64 s[4:5], -1
	v_mul_f32_e32 v2, 0x4f7ffffe, v2
	v_cvt_u32_f32_e32 v2, v2
	v_mul_lo_u32 v3, v3, v2
	v_mul_hi_u32 v3, v2, v3
	v_add_u32_e32 v2, v2, v3
	v_mul_hi_u32 v2, v1, v2
	v_mul_lo_u32 v3, v2, v0
	v_sub_u32_e32 v3, v1, v3
	v_cmp_ge_u32_e32 vcc, v3, v0
	v_add_u32_e32 v4, 1, v2
	v_add_u32_e32 v1, 1, v1
	v_cndmask_b32_e32 v2, v2, v4, vcc
	v_sub_u32_e32 v4, v3, v0
	v_cndmask_b32_e32 v3, v3, v4, vcc
	v_cmp_ge_u32_e32 vcc, v3, v0
	v_add_u32_e32 v3, 1, v2
	s_nop 0
	v_cndmask_b32_e32 v2, v2, v3, vcc
	v_mul_lo_u32 v3, v0, v2
	v_add_u32_e32 v0, v3, v0
	v_cmp_ne_u32_e32 vcc, v1, v0
	v_mov_b64_e32 v[0:1], s[2:3]
	s_and_saveexec_b64 s[2:3], vcc
	s_cbranch_execz .LBB0_343
	v_readlane_b32 s4, v253, 13
	v_readlane_b32 s5, v253, 14
	s_mov_b64 s[6:7], 0
	s_nop 3
	global_load_dword v0, v129, s[4:5] sc1
	s_waitcnt vmcnt(0)
	v_cmp_eq_u32_e32 vcc, v0, v2
	s_and_saveexec_b64 s[4:5], vcc
	s_cbranch_execz .LBB0_342
	s_mov_b32 s17, 1
	s_branch .LBB0_335

; __device__ __forceinline__ unsigned xb_ld(unsigned* p)              { return __hip_atomic_load(p, __ATOMIC_RELAXED, __HIP_MEMORY_SCOPE_AGENT); }
; __device__ __forceinline__ unsigned xb_add(unsigned* p, unsigned v) { return __hip_atomic_fetch_add(p, v, __ATOMIC_RELAXED, __HIP_MEMORY_SCOPE_AGENT); }
; #define XB_SPIN(cond, bar) do { unsigned _sp = 0; while (cond) { __builtin_amdgcn_s_sleep(1); \
;     if ((++_sp & 255u) == 0u) { if (xb_ld(&(bar)[XB_TMO])) break; if (_sp > XB_SPIN_CAP) { atomicAdd(&(bar)[XB_TMO], 1u); break; } } } } while (0)
; __device__ __forceinline__ void xcd_barrier(const XcdBarrier& b) {
;     ...
;             const unsigned og = xb_add(&bar[XB_TOP], 1u);
;             const unsigned tg = og / nx;
;             if (og + 1u == (tg + 1u) * nx) xb_add(&bar[XB_TOPGEN], 1u);
;             else XB_SPIN(xb_ld(&bar[XB_TOPGEN]) == tg, bar);
.LBB0_339:
	v_readlane_b32 s10, v253, 13
	v_readlane_b32 s11, v253, 14
	s_add_i32 s17, s17, 1
	s_mov_b64 s[12:13], -1
	s_nop 2
	global_load_dword v0, v129, s[10:11] sc1
	s_waitcnt vmcnt(0)
	v_cmp_ne_u32_e32 vcc, v0, v2
	s_orn2_b64 s[10:11], vcc, exec
	s_branch .LBB0_334
